# mixed_fold barrier replaced by signal: fold on WGs 224-255 with write-through stores, WGs<16 check the counter at P6 start
# speedup vs baseline: 1.0643x; 1.0069x over previous
; #define LAS __attribute__((address_space(3)))
; __device__ __forceinline__ KP kargs() { KP k = (KP)__builtin_amdgcn_kernarg_segment_ptr(); asm volatile("" : "+s"(k)); return k; }
; __device__ __forceinline__ int tid_() { int t = threadIdx.x; asm volatile("" : "+v"(t)); return t; }
; __device__ __forceinline__ unsigned xb_ld(unsigned* p)              { return __hip_atomic_load(p, __ATOMIC_RELAXED, __HIP_MEMORY_SCOPE_AGENT); }
; __device__ __forceinline__ unsigned xb_add(unsigned* p, unsigned v) { return __hip_atomic_fetch_add(p, v, __ATOMIC_RELAXED, __HIP_MEMORY_SCOPE_AGENT); }
; __device__ __forceinline__ unsigned xb_xcc_id() { return (unsigned)__builtin_amdgcn_s_getreg((3 << 11) | 20) & 0xFu; }
; __device__ __forceinline__ void grid_barrier(LAS unsigned char* lds) {
;     asm volatile("s_waitcnt vmcnt(0)" ::: "memory");
;     __syncthreads();
;     if (tid_() == 0) {
;         unsigned* bar = (unsigned*)(kargs()->ws + WS_BAR);
;         volatile LAS unsigned* st = (volatile LAS unsigned*)(lds + LDS_BAR_OFF);
;         const unsigned x = xb_xcc_id();
;         __builtin_amdgcn_s_waitcnt(0);
;         unsigned nloc = st[0], nx = st[1];
;         if (nloc == 0u) { xcd_barrier_complete(bar, x, nloc, nx); st[0] = nloc; st[1] = nx; }
;         const unsigned old = xb_add(&bar[XB_XSUB(x)], 1u);
;         const unsigned gen = old / nloc;
;         if (old + 1u == (gen + 1u) * nloc) {
;             __builtin_amdgcn_fence(__ATOMIC_RELEASE, "agent");
;             asm volatile("s_waitcnt vmcnt(0)" ::: "memory");
;             const unsigned og = xb_add(&bar[XB_TOP], 1u);
;             const unsigned tg = og / nx;
;             if (og + 1u == (tg + 1u) * nx) xb_add(&bar[XB_TOPGEN], 1u);
;             else XB_SPIN(xb_ld(&bar[XB_TOPGEN]) == tg, bar);
;             __builtin_amdgcn_fence(__ATOMIC_ACQUIRE, "agent");
;             xb_add(&bar[XB_XGEN(x)], 1u);
;             asm volatile("s_waitcnt vmcnt(0)" ::: "memory");
;         } else {
;             XB_SPIN(xb_ld(&bar[XB_XGEN(x)]) == gen, bar);
;             __builtin_amdgcn_fence(__ATOMIC_ACQUIRE, "agent");
;             asm volatile("s_waitcnt vmcnt(0)" ::: "memory");
;         }
;     }
;     __syncthreads();
; }
; __global__ void __launch_bounds__(512, 2) fwd_megakernel(Params pv) {
;     ...
;         norm_phase(kargs(), l == 0, 11);
;         grid_barrier(lds);
.LBB0_88:
	s_waitcnt vmcnt(0)
	v_mov_b32_e32 v0, v209
	s_barrier
	s_nop 0
	v_cmp_eq_u32_e32 vcc, 0, v0
	s_and_saveexec_b64 s[4:5], vcc
	s_cbranch_execz .LBB0_140
	s_cmp_eq_u32 s56, 0
	s_cbranch_scc1 .Lfb1_orig
	v_readlane_b32 s12, v255, 8
	v_readlane_b32 s13, v255, 9
	v_mov_b32_e32 v19, 1
	v_mov_b32_e32 v22, 0
	s_lshl_b32 s35, s56, 4
	s_add_i32 s35, s35, 15872
	s_add_u32 s12, s12, s35
	s_addc_u32 s13, s13, 0
	global_atomic_add v22, v19, s[12:13]
	s_waitcnt vmcnt(0)
	s_branch .LBB0_140

;     __device__ __forceinline__ void operator()(const f32x4 (&acc)[2][2][4][2], const Unit& u, int wr, int wc, int fr, int fq) const {
;         const int rbase = u.pm * BM + wr * 64 + fr;
;         if (u.pn >= 16) {
.LBB0_164:
	s_cmp_lg_u32 s48, 0
	s_cbranch_scc1 .Lfw_p2_done
	s_cmp_eq_u32 s56, 0
	s_cbranch_scc1 .Lfw_p2_done
	s_lshl_b32 s14, s56, 4
	s_add_u32 s12, s64, 0x13ce3e00
	s_addc_u32 s13, s65, 0
	s_add_u32 s12, s12, s14
	s_addc_u32 s13, s13, 0
	v_mov_b32_e32 v191, 0
	s_mov_b32 s14, 0

; #define LAS __attribute__((address_space(3)))
; __device__ __forceinline__ KP kargs() { KP k = (KP)__builtin_amdgcn_kernarg_segment_ptr(); asm volatile("" : "+s"(k)); return k; }
; __device__ __forceinline__ int tid_() { int t = threadIdx.x; asm volatile("" : "+v"(t)); return t; }
; __device__ __forceinline__ unsigned xb_ld(unsigned* p)              { return __hip_atomic_load(p, __ATOMIC_RELAXED, __HIP_MEMORY_SCOPE_AGENT); }
; __device__ __forceinline__ unsigned xb_add(unsigned* p, unsigned v) { return __hip_atomic_fetch_add(p, v, __ATOMIC_RELAXED, __HIP_MEMORY_SCOPE_AGENT); }
; __device__ __forceinline__ unsigned xb_xcc_id() { return (unsigned)__builtin_amdgcn_s_getreg((3 << 11) | 20) & 0xFu; }
; __device__ __forceinline__ void grid_barrier(LAS unsigned char* lds) {
;     asm volatile("s_waitcnt vmcnt(0)" ::: "memory");
;     __syncthreads();
;     if (tid_() == 0) {
;         unsigned* bar = (unsigned*)(kargs()->ws + WS_BAR);
;         volatile LAS unsigned* st = (volatile LAS unsigned*)(lds + LDS_BAR_OFF);
;         const unsigned x = xb_xcc_id();
;         __builtin_amdgcn_s_waitcnt(0);
;         unsigned nloc = st[0], nx = st[1];
;         if (nloc == 0u) { xcd_barrier_complete(bar, x, nloc, nx); st[0] = nloc; st[1] = nx; }
;         const unsigned old = xb_add(&bar[XB_XSUB(x)], 1u);
;         const unsigned gen = old / nloc;
;         if (old + 1u == (gen + 1u) * nloc) {
;             __builtin_amdgcn_fence(__ATOMIC_RELEASE, "agent");
;             asm volatile("s_waitcnt vmcnt(0)" ::: "memory");
;             const unsigned og = xb_add(&bar[XB_TOP], 1u);
;             const unsigned tg = og / nx;
;             if (og + 1u == (tg + 1u) * nx) xb_add(&bar[XB_TOPGEN], 1u);
;             else XB_SPIN(xb_ld(&bar[XB_TOPGEN]) == tg, bar);
;             __builtin_amdgcn_fence(__ATOMIC_ACQUIRE, "agent");
;             xb_add(&bar[XB_XGEN(x)], 1u);
;             asm volatile("s_waitcnt vmcnt(0)" ::: "memory");
;         } else {
;             XB_SPIN(xb_ld(&bar[XB_XGEN(x)]) == gen, bar);
;             __builtin_amdgcn_fence(__ATOMIC_ACQUIRE, "agent");
;             asm volatile("s_waitcnt vmcnt(0)" ::: "memory");
;         }
;     }
;     __syncthreads();
; }
; __global__ void __launch_bounds__(512, 2) fwd_megakernel(Params pv) {
;     ...
;         grid_barrier(lds);
.LBB0_264:
	s_waitcnt vmcnt(0)
	v_mov_b32_e32 v0, v209
	s_waitcnt vmcnt(0)
	s_barrier
	s_nop 0
	v_cmp_eq_u32_e32 vcc, 0, v0
	s_and_saveexec_b64 s[4:5], vcc
	s_movk_i32 s0, 0x400
	s_mov_b32 s1, 0xfe03f81
	s_mov_b32 s20, 0x800000
	v_readlane_b32 s52, v255, 3
	v_readlane_b32 s50, v255, 4
	s_movk_i32 s23, 0x3000
	s_movk_i32 s43, 0x2000
	s_movk_i32 s21, 0x810
	s_cbranch_execz .LBB0_316
	v_readlane_b32 s12, v255, 8
	v_readlane_b32 s13, v255, 9
	v_mov_b32_e32 v18, 0x20000
	ds_read2_b32 v[20:21], v18 offset1:1
	s_getreg_b32 s14, hwreg(HW_REG_XCC_ID, 0, 4)
	s_and_b32 s14, s14, 15
	s_mul_i32 s32, s56, 8
	s_add_i32 s32, s32, 1
	s_add_i32 s34, s32, 1
	v_mov_b32_e32 v19, 1
	v_mov_b32_e32 v22, 0
	s_waitcnt lgkmcnt(0)
	v_readfirstlane_b32 s24, v20
	v_readfirstlane_b32 s25, v21
	s_lshl_b32 s35, s14, 8
	s_add_u32 s70, s12, s35
	s_addc_u32 s71, s13, 0
	s_add_u32 s72, s70, 0x2400
	s_addc_u32 s73, s71, 0
	s_add_u32 s70, s70, 0x1400
	s_addc_u32 s71, s71, 0
	global_atomic_add v23, v22, v19, s[70:71] sc0
	s_mul_i32 s57, s34, s24
	s_waitcnt vmcnt(0)
	v_readfirstlane_b32 s44, v23
	s_nop 3
	s_add_i32 s44, s44, 1
	s_cmp_lg_u32 s44, s57
	s_cbranch_scc1 .Lfb2_spin
	buffer_wbl2 sc1
	s_waitcnt vmcnt(0)
	s_add_u32 s98, s12, 0x3400
	s_addc_u32 s99, s13, 0
	global_atomic_add v23, v22, v19, s[98:99] sc0
	s_mul_i32 s57, s34, s25
	s_waitcnt vmcnt(0)
	v_readfirstlane_b32 s44, v23
	s_nop 3
	s_add_i32 s44, s44, 1
	s_cmp_lg_u32 s44, s57
	s_cbranch_scc1 .Lfb2_spin
	global_atomic_add v22, v19, s[98:99] offset:256
	s_add_u32 s98, s12, 0x2400
	s_addc_u32 s99, s13, 0
	global_atomic_add v22, v19, s[98:99]
	global_atomic_add v22, v19, s[98:99] offset:256
	global_atomic_add v22, v19, s[98:99] offset:512
	global_atomic_add v22, v19, s[98:99] offset:768
	global_atomic_add v22, v19, s[98:99] offset:1024
	global_atomic_add v22, v19, s[98:99] offset:1280
	global_atomic_add v22, v19, s[98:99] offset:1536
	global_atomic_add v22, v19, s[98:99] offset:1792
	global_atomic_add v22, v19, s[98:99] offset:2048
	global_atomic_add v22, v19, s[98:99] offset:2304
	global_atomic_add v22, v19, s[98:99] offset:2560
	global_atomic_add v22, v19, s[98:99] offset:2816
	global_atomic_add v22, v19, s[98:99] offset:3072
	global_atomic_add v22, v19, s[98:99] offset:3328
	global_atomic_add v22, v19, s[98:99] offset:3584
	global_atomic_add v22, v19, s[98:99] offset:3840

; #define LAS __attribute__((address_space(3)))
; __device__ __forceinline__ KP kargs() { KP k = (KP)__builtin_amdgcn_kernarg_segment_ptr(); asm volatile("" : "+s"(k)); return k; }
; __device__ __forceinline__ int tid_() { int t = threadIdx.x; asm volatile("" : "+v"(t)); return t; }
; __device__ __forceinline__ unsigned xb_ld(unsigned* p)              { return __hip_atomic_load(p, __ATOMIC_RELAXED, __HIP_MEMORY_SCOPE_AGENT); }
; __device__ __forceinline__ unsigned xb_add(unsigned* p, unsigned v) { return __hip_atomic_fetch_add(p, v, __ATOMIC_RELAXED, __HIP_MEMORY_SCOPE_AGENT); }
; __device__ __forceinline__ unsigned xb_xcc_id() { return (unsigned)__builtin_amdgcn_s_getreg((3 << 11) | 20) & 0xFu; }
; __device__ __forceinline__ void grid_barrier(LAS unsigned char* lds) {
;     asm volatile("s_waitcnt vmcnt(0)" ::: "memory");
;     __syncthreads();
;     if (tid_() == 0) {
;         unsigned* bar = (unsigned*)(kargs()->ws + WS_BAR);
;         volatile LAS unsigned* st = (volatile LAS unsigned*)(lds + LDS_BAR_OFF);
;         const unsigned x = xb_xcc_id();
;         __builtin_amdgcn_s_waitcnt(0);
;         unsigned nloc = st[0], nx = st[1];
;         if (nloc == 0u) { xcd_barrier_complete(bar, x, nloc, nx); st[0] = nloc; st[1] = nx; }
;         const unsigned old = xb_add(&bar[XB_XSUB(x)], 1u);
;         const unsigned gen = old / nloc;
;         if (old + 1u == (gen + 1u) * nloc) {
;             __builtin_amdgcn_fence(__ATOMIC_RELEASE, "agent");
;             asm volatile("s_waitcnt vmcnt(0)" ::: "memory");
;             const unsigned og = xb_add(&bar[XB_TOP], 1u);
;             const unsigned tg = og / nx;
;             if (og + 1u == (tg + 1u) * nx) xb_add(&bar[XB_TOPGEN], 1u);
;             else XB_SPIN(xb_ld(&bar[XB_TOPGEN]) == tg, bar);
;             __builtin_amdgcn_fence(__ATOMIC_ACQUIRE, "agent");
;             xb_add(&bar[XB_XGEN(x)], 1u);
;             asm volatile("s_waitcnt vmcnt(0)" ::: "memory");
;         } else {
;             XB_SPIN(xb_ld(&bar[XB_XGEN(x)]) == gen, bar);
;             __builtin_amdgcn_fence(__ATOMIC_ACQUIRE, "agent");
;             asm volatile("s_waitcnt vmcnt(0)" ::: "memory");
;         }
;     }
;     __syncthreads();
; }
; __global__ void __launch_bounds__(512, 2) fwd_megakernel(Params pv) {
;     ...
;         grid_barrier(lds);
.LBB0_357:
	s_waitcnt vmcnt(0)
	v_mov_b32_e32 v0, v209
	s_waitcnt lgkmcnt(0)
	s_barrier
	s_nop 0
	v_cmp_eq_u32_e32 vcc, 0, v0
	s_and_saveexec_b64 s[4:5], vcc
	s_cbranch_execz .LBB0_409
	v_readlane_b32 s12, v255, 8
	v_readlane_b32 s13, v255, 9
	v_mov_b32_e32 v18, 0x20000
	ds_read2_b32 v[20:21], v18 offset1:1
	s_getreg_b32 s14, hwreg(HW_REG_XCC_ID, 0, 4)
	s_and_b32 s14, s14, 15
	s_mul_i32 s32, s56, 8
	s_add_i32 s32, s32, 2
	s_add_i32 s34, s32, 1
	v_mov_b32_e32 v19, 1
	v_mov_b32_e32 v22, 0
	s_waitcnt lgkmcnt(0)
	v_readfirstlane_b32 s24, v20
	v_readfirstlane_b32 s25, v21
	s_lshl_b32 s35, s14, 8
	s_add_u32 s70, s12, s35
	s_addc_u32 s71, s13, 0
	s_add_u32 s72, s70, 0x2400
	s_addc_u32 s73, s71, 0
	s_add_u32 s70, s70, 0x1400
	s_addc_u32 s71, s71, 0
	global_atomic_add v23, v22, v19, s[70:71] sc0
	s_mul_i32 s57, s34, s24
	s_waitcnt vmcnt(0)
	v_readfirstlane_b32 s44, v23
	s_nop 3
	s_add_i32 s44, s44, 1
	s_cmp_lg_u32 s44, s57
	s_cbranch_scc1 .Lfb3_spin
	buffer_wbl2 sc1
	s_waitcnt vmcnt(0)
	s_add_u32 s98, s12, 0x3400
	s_addc_u32 s99, s13, 0
	global_atomic_add v23, v22, v19, s[98:99] sc0
	s_mul_i32 s57, s34, s25
	s_waitcnt vmcnt(0)
	v_readfirstlane_b32 s44, v23
	s_nop 3
	s_add_i32 s44, s44, 1
	s_cmp_lg_u32 s44, s57
	s_cbranch_scc1 .Lfb3_spin
	global_atomic_add v22, v19, s[98:99] offset:256
	s_add_u32 s98, s12, 0x2400
	s_addc_u32 s99, s13, 0
	global_atomic_add v22, v19, s[98:99]
	global_atomic_add v22, v19, s[98:99] offset:256
	global_atomic_add v22, v19, s[98:99] offset:512
	global_atomic_add v22, v19, s[98:99] offset:768
	global_atomic_add v22, v19, s[98:99] offset:1024
	global_atomic_add v22, v19, s[98:99] offset:1280
	global_atomic_add v22, v19, s[98:99] offset:1536
	global_atomic_add v22, v19, s[98:99] offset:1792
	global_atomic_add v22, v19, s[98:99] offset:2048
	global_atomic_add v22, v19, s[98:99] offset:2304
	global_atomic_add v22, v19, s[98:99] offset:2560
	global_atomic_add v22, v19, s[98:99] offset:2816
	global_atomic_add v22, v19, s[98:99] offset:3072
	global_atomic_add v22, v19, s[98:99] offset:3328
	global_atomic_add v22, v19, s[98:99] offset:3584
	global_atomic_add v22, v19, s[98:99] offset:3840

; #define LAS __attribute__((address_space(3)))
; __device__ __forceinline__ KP kargs() { KP k = (KP)__builtin_amdgcn_kernarg_segment_ptr(); asm volatile("" : "+s"(k)); return k; }
; __device__ __forceinline__ int tid_() { int t = threadIdx.x; asm volatile("" : "+v"(t)); return t; }
; __device__ __forceinline__ unsigned xb_ld(unsigned* p)              { return __hip_atomic_load(p, __ATOMIC_RELAXED, __HIP_MEMORY_SCOPE_AGENT); }
; __device__ __forceinline__ unsigned xb_add(unsigned* p, unsigned v) { return __hip_atomic_fetch_add(p, v, __ATOMIC_RELAXED, __HIP_MEMORY_SCOPE_AGENT); }
; __device__ __forceinline__ unsigned xb_xcc_id() { return (unsigned)__builtin_amdgcn_s_getreg((3 << 11) | 20) & 0xFu; }
; __device__ __forceinline__ void grid_barrier(LAS unsigned char* lds) {
;     asm volatile("s_waitcnt vmcnt(0)" ::: "memory");
;     __syncthreads();
;     if (tid_() == 0) {
;         unsigned* bar = (unsigned*)(kargs()->ws + WS_BAR);
;         volatile LAS unsigned* st = (volatile LAS unsigned*)(lds + LDS_BAR_OFF);
;         const unsigned x = xb_xcc_id();
;         __builtin_amdgcn_s_waitcnt(0);
;         unsigned nloc = st[0], nx = st[1];
;         if (nloc == 0u) { xcd_barrier_complete(bar, x, nloc, nx); st[0] = nloc; st[1] = nx; }
;         const unsigned old = xb_add(&bar[XB_XSUB(x)], 1u);
;         const unsigned gen = old / nloc;
;         if (old + 1u == (gen + 1u) * nloc) {
;             __builtin_amdgcn_fence(__ATOMIC_RELEASE, "agent");
;             asm volatile("s_waitcnt vmcnt(0)" ::: "memory");
;             const unsigned og = xb_add(&bar[XB_TOP], 1u);
;             const unsigned tg = og / nx;
;             if (og + 1u == (tg + 1u) * nx) xb_add(&bar[XB_TOPGEN], 1u);
;             else XB_SPIN(xb_ld(&bar[XB_TOPGEN]) == tg, bar);
;             __builtin_amdgcn_fence(__ATOMIC_ACQUIRE, "agent");
;             xb_add(&bar[XB_XGEN(x)], 1u);
;             asm volatile("s_waitcnt vmcnt(0)" ::: "memory");
;         } else {
;             XB_SPIN(xb_ld(&bar[XB_XGEN(x)]) == gen, bar);
;             __builtin_amdgcn_fence(__ATOMIC_ACQUIRE, "agent");
;             asm volatile("s_waitcnt vmcnt(0)" ::: "memory");
;         }
;     }
;     __syncthreads();
; }
; __global__ void __launch_bounds__(512, 2) fwd_megakernel(Params pv) {
;     ...
;         grid_barrier(lds);
.LBB0_426:
	s_or_b64 exec, exec, s[8:9]
	s_waitcnt vmcnt(0)
	v_mov_b32_e32 v0, v209
	s_barrier
	s_nop 0
	v_cmp_eq_u32_e32 vcc, 0, v0
	s_and_saveexec_b64 s[4:5], vcc
	s_cbranch_execz .LBB0_478
	v_readlane_b32 s12, v255, 8
	v_readlane_b32 s13, v255, 9
	v_mov_b32_e32 v18, 0x20000
	ds_read2_b32 v[20:21], v18 offset1:1
	s_getreg_b32 s14, hwreg(HW_REG_XCC_ID, 0, 4)
	s_and_b32 s14, s14, 15
	s_mul_i32 s32, s56, 8
	s_add_i32 s32, s32, 3
	s_add_i32 s34, s32, 1
	v_mov_b32_e32 v19, 1
	v_mov_b32_e32 v22, 0
	s_waitcnt lgkmcnt(0)
	v_readfirstlane_b32 s24, v20
	v_readfirstlane_b32 s25, v21
	s_lshl_b32 s35, s14, 8
	s_add_u32 s70, s12, s35
	s_addc_u32 s71, s13, 0
	s_add_u32 s72, s70, 0x2400
	s_addc_u32 s73, s71, 0
	s_add_u32 s70, s70, 0x1400
	s_addc_u32 s71, s71, 0
	global_atomic_add v23, v22, v19, s[70:71] sc0
	s_mul_i32 s57, s34, s24
	s_waitcnt vmcnt(0)
	v_readfirstlane_b32 s44, v23
	s_nop 3
	s_add_i32 s44, s44, 1
	s_cmp_lg_u32 s44, s57
	s_cbranch_scc1 .Lfb4_spin
	buffer_wbl2 sc1
	s_waitcnt vmcnt(0)
	s_add_u32 s98, s12, 0x3400
	s_addc_u32 s99, s13, 0
	global_atomic_add v23, v22, v19, s[98:99] sc0
	s_mul_i32 s57, s34, s25
	s_waitcnt vmcnt(0)
	v_readfirstlane_b32 s44, v23
	s_nop 3
	s_add_i32 s44, s44, 1
	s_cmp_lg_u32 s44, s57
	s_cbranch_scc1 .Lfb4_spin
	global_atomic_add v22, v19, s[98:99] offset:256
	s_add_u32 s98, s12, 0x2400
	s_addc_u32 s99, s13, 0
	global_atomic_add v22, v19, s[98:99]
	global_atomic_add v22, v19, s[98:99] offset:256
	global_atomic_add v22, v19, s[98:99] offset:512
	global_atomic_add v22, v19, s[98:99] offset:768
	global_atomic_add v22, v19, s[98:99] offset:1024
	global_atomic_add v22, v19, s[98:99] offset:1280
	global_atomic_add v22, v19, s[98:99] offset:1536
	global_atomic_add v22, v19, s[98:99] offset:1792
	global_atomic_add v22, v19, s[98:99] offset:2048
	global_atomic_add v22, v19, s[98:99] offset:2304
	global_atomic_add v22, v19, s[98:99] offset:2560
	global_atomic_add v22, v19, s[98:99] offset:2816
	global_atomic_add v22, v19, s[98:99] offset:3072
	global_atomic_add v22, v19, s[98:99] offset:3328
	global_atomic_add v22, v19, s[98:99] offset:3584
	global_atomic_add v22, v19, s[98:99] offset:3840

; #define LAS __attribute__((address_space(3)))
; __device__ __forceinline__ KP kargs() { KP k = (KP)__builtin_amdgcn_kernarg_segment_ptr(); asm volatile("" : "+s"(k)); return k; }
; __device__ __forceinline__ int tid_() { int t = threadIdx.x; asm volatile("" : "+v"(t)); return t; }
; __device__ __forceinline__ unsigned xb_ld(unsigned* p)              { return __hip_atomic_load(p, __ATOMIC_RELAXED, __HIP_MEMORY_SCOPE_AGENT); }
; __device__ __forceinline__ unsigned xb_add(unsigned* p, unsigned v) { return __hip_atomic_fetch_add(p, v, __ATOMIC_RELAXED, __HIP_MEMORY_SCOPE_AGENT); }
; __device__ __forceinline__ unsigned xb_xcc_id() { return (unsigned)__builtin_amdgcn_s_getreg((3 << 11) | 20) & 0xFu; }
; __device__ __forceinline__ void grid_barrier(LAS unsigned char* lds) {
;     asm volatile("s_waitcnt vmcnt(0)" ::: "memory");
;     __syncthreads();
;     if (tid_() == 0) {
;         unsigned* bar = (unsigned*)(kargs()->ws + WS_BAR);
;         volatile LAS unsigned* st = (volatile LAS unsigned*)(lds + LDS_BAR_OFF);
;         const unsigned x = xb_xcc_id();
;         __builtin_amdgcn_s_waitcnt(0);
;         unsigned nloc = st[0], nx = st[1];
;         if (nloc == 0u) { xcd_barrier_complete(bar, x, nloc, nx); st[0] = nloc; st[1] = nx; }
;         const unsigned old = xb_add(&bar[XB_XSUB(x)], 1u);
;         const unsigned gen = old / nloc;
;         if (old + 1u == (gen + 1u) * nloc) {
;             __builtin_amdgcn_fence(__ATOMIC_RELEASE, "agent");
;             asm volatile("s_waitcnt vmcnt(0)" ::: "memory");
;             const unsigned og = xb_add(&bar[XB_TOP], 1u);
;             const unsigned tg = og / nx;
;             if (og + 1u == (tg + 1u) * nx) xb_add(&bar[XB_TOPGEN], 1u);
;             else XB_SPIN(xb_ld(&bar[XB_TOPGEN]) == tg, bar);
;             __builtin_amdgcn_fence(__ATOMIC_ACQUIRE, "agent");
;             xb_add(&bar[XB_XGEN(x)], 1u);
;             asm volatile("s_waitcnt vmcnt(0)" ::: "memory");
;         } else {
;             XB_SPIN(xb_ld(&bar[XB_XGEN(x)]) == gen, bar);
;             __builtin_amdgcn_fence(__ATOMIC_ACQUIRE, "agent");
;             asm volatile("s_waitcnt vmcnt(0)" ::: "memory");
;         }
;     }
;     __syncthreads();
; }
; __global__ void __launch_bounds__(512, 2) fwd_megakernel(Params pv) {
;     ...
;         grid_barrier(lds);
.LBB0_587:
	s_waitcnt vmcnt(0)
	v_mov_b32_e32 v0, v209
	s_waitcnt vmcnt(0) lgkmcnt(0)
	s_barrier
	s_nop 0
	v_cmp_eq_u32_e32 vcc, 0, v0
	s_and_saveexec_b64 s[4:5], vcc
	s_mov_b64 s[74:75], 0x48000
	s_cbranch_execz .LBB0_639
	v_readlane_b32 s12, v255, 8
	v_readlane_b32 s13, v255, 9
	v_mov_b32_e32 v18, 0x20000
	ds_read2_b32 v[20:21], v18 offset1:1
	s_getreg_b32 s14, hwreg(HW_REG_XCC_ID, 0, 4)
	s_and_b32 s14, s14, 15
	s_mul_i32 s32, s56, 8
	s_add_i32 s32, s32, 4
	s_add_i32 s34, s32, 1
	v_mov_b32_e32 v19, 1
	v_mov_b32_e32 v22, 0
	s_waitcnt lgkmcnt(0)
	v_readfirstlane_b32 s24, v20
	v_readfirstlane_b32 s25, v21
	s_lshl_b32 s35, s14, 8
	s_add_u32 s70, s12, s35
	s_addc_u32 s71, s13, 0
	s_add_u32 s72, s70, 0x2400
	s_addc_u32 s73, s71, 0
	s_add_u32 s70, s70, 0x1400
	s_addc_u32 s71, s71, 0
	global_atomic_add v23, v22, v19, s[70:71] sc0
	s_mul_i32 s57, s34, s24
	s_waitcnt vmcnt(0)
	v_readfirstlane_b32 s44, v23
	s_nop 3
	s_add_i32 s44, s44, 1
	s_cmp_lg_u32 s44, s57
	s_cbranch_scc1 .Lfb5_spin
	buffer_wbl2 sc1
	s_waitcnt vmcnt(0)
	s_add_u32 s98, s12, 0x3400
	s_addc_u32 s99, s13, 0
	global_atomic_add v23, v22, v19, s[98:99] sc0
	s_mul_i32 s57, s34, s25
	s_waitcnt vmcnt(0)
	v_readfirstlane_b32 s44, v23
	s_nop 3
	s_add_i32 s44, s44, 1
	s_cmp_lg_u32 s44, s57
	s_cbranch_scc1 .Lfb5_spin
	global_atomic_add v22, v19, s[98:99] offset:256
	s_add_u32 s98, s12, 0x2400
	s_addc_u32 s99, s13, 0
	global_atomic_add v22, v19, s[98:99]
	global_atomic_add v22, v19, s[98:99] offset:256
	global_atomic_add v22, v19, s[98:99] offset:512
	global_atomic_add v22, v19, s[98:99] offset:768
	global_atomic_add v22, v19, s[98:99] offset:1024
	global_atomic_add v22, v19, s[98:99] offset:1280
	global_atomic_add v22, v19, s[98:99] offset:1536
	global_atomic_add v22, v19, s[98:99] offset:1792
	global_atomic_add v22, v19, s[98:99] offset:2048
	global_atomic_add v22, v19, s[98:99] offset:2304
	global_atomic_add v22, v19, s[98:99] offset:2560
	global_atomic_add v22, v19, s[98:99] offset:2816
	global_atomic_add v22, v19, s[98:99] offset:3072
	global_atomic_add v22, v19, s[98:99] offset:3328
	global_atomic_add v22, v19, s[98:99] offset:3584
	global_atomic_add v22, v19, s[98:99] offset:3840

; __device__ __forceinline__ int tid_() { int t = threadIdx.x; asm volatile("" : "+v"(t)); return t; }
; __device__ __forceinline__ int bid_() { int t = blockIdx.x; asm volatile("" : "+s"(t)); return t; }
; __device__ __forceinline__ int gdim_() { int t = gridDim.x; asm volatile("" : "+s"(t)); return t; }
; __device__ __forceinline__ unsigned cvt_pk_bf16(float lo, float hi) { unsigned r; asm volatile("v_cvt_pk_bf16_f32 %0, %1, %2" : "=v"(r) : "v"(lo), "v"(hi)); return r; }
; __device__ __forceinline__ void mixed_fold_phase(KP p) {
;     const int tid = tid_(), lane = tid & 63, wave = __builtin_amdgcn_readfirstlane(tid >> 6);
;     const int gw = bid_() * 8 + wave, NGW = gdim_() * 8;
;     bf16_t* P = (bf16_t*)(p->ws + WS_BIG);
;     for (int r = gw; r < 256; r += NGW) {
;         const f32x4* sl = (const f32x4*)(p->ws + WS_SLAB) + (size_t)r * (D / 4) + lane;
;         f32x4 v[4];
; #pragma unroll
;         for (int j = 0; j < 4; ++j) v[j] = sl[64 * j];
;         for (int q = 1; q < 8; ++q) {
; #pragma unroll
;             for (int j = 0; j < 4; ++j) v[j] += sl[(size_t)q * 256 * (D / 4) + 64 * j]; }
;         u32x2* o8 = (u32x2*)(P + (size_t)(64 * 256 + r) * DP + C_MIX) + lane;
; #pragma unroll
;         for (int j = 0; j < 4; ++j) { u32x2 w; w.x = cvt_pk_bf16(v[j][0], v[j][1]); w.y = cvt_pk_bf16(v[j][2], v[j][3]); o8[64 * j] = w; }
;     }
; }
.LBB0_639:
	s_or_b64 exec, exec, s[4:5]
	s_mov_b64 s[8:9], s[94:95]
	v_mov_b32_e32 v0, v209
	s_mov_b32 s5, s2
	s_waitcnt lgkmcnt(0)
	s_barrier
	v_readfirstlane_b32 s4, v0
	s_ashr_i32 s4, s4, 6
	s_sub_i32 s5, s5, 0xe0
	s_lshl_b32 s5, s5, 3
	s_add_i32 s4, s5, s4
	s_mov_b32 s5, s3
	s_cmpk_lt_i32 s4, 0
	s_cbranch_scc1 .LBB0_642
	s_load_dwordx2 s[8:9], s[8:9], 0xe8
	s_lshl_b32 s6, s5, 3
	s_ashr_i32 s7, s6, 31
	s_lshl_b64 s[10:11], s[6:7], 12
	v_and_b32_e32 v2, 63, v0
	v_lshlrev_b32_e32 v3, 4, v2
	v_lshlrev_b32_e32 v5, 3, v2
	s_waitcnt lgkmcnt(0)
.LBB0_641:
	s_lshl_b32 s12, s4, 12
	s_add_u32 s12, s8, s12
	s_addc_u32 s13, s9, 0
	s_add_u32 s12, s12, 0x1a3ac000
	s_addc_u32 s13, s13, 0
	global_load_dwordx4 v[20:23], v3, s[12:13]
	global_load_dwordx4 v[24:27], v3, s[12:13] offset:1024
	global_load_dwordx4 v[28:31], v3, s[12:13] offset:2048
	global_load_dwordx4 v[32:35], v3, s[12:13] offset:3072
	s_add_u32 s12, s12, 0x100000
	s_addc_u32 s13, s13, 0
	global_load_dwordx4 v[36:39], v3, s[12:13]
	global_load_dwordx4 v[40:43], v3, s[12:13] offset:1024
	global_load_dwordx4 v[44:47], v3, s[12:13] offset:2048
	global_load_dwordx4 v[48:51], v3, s[12:13] offset:3072
	s_add_u32 s12, s12, 0x100000
	s_addc_u32 s13, s13, 0
	global_load_dwordx4 v[52:55], v3, s[12:13]
	global_load_dwordx4 v[56:59], v3, s[12:13] offset:1024
	global_load_dwordx4 v[60:63], v3, s[12:13] offset:2048
	global_load_dwordx4 v[64:67], v3, s[12:13] offset:3072
	s_add_u32 s12, s12, 0x100000
	s_addc_u32 s13, s13, 0
	global_load_dwordx4 v[68:71], v3, s[12:13]
	global_load_dwordx4 v[72:75], v3, s[12:13] offset:1024
	global_load_dwordx4 v[76:79], v3, s[12:13] offset:2048
	global_load_dwordx4 v[80:83], v3, s[12:13] offset:3072
	s_add_u32 s12, s12, 0x100000
	s_addc_u32 s13, s13, 0
	global_load_dwordx4 v[84:87], v3, s[12:13]
	global_load_dwordx4 v[88:91], v3, s[12:13] offset:1024
	global_load_dwordx4 v[92:95], v3, s[12:13] offset:2048
	global_load_dwordx4 v[96:99], v3, s[12:13] offset:3072
	s_add_u32 s12, s12, 0x100000
	s_addc_u32 s13, s13, 0
	global_load_dwordx4 v[100:103], v3, s[12:13]
	global_load_dwordx4 v[104:107], v3, s[12:13] offset:1024
	global_load_dwordx4 v[108:111], v3, s[12:13] offset:2048
	global_load_dwordx4 v[112:115], v3, s[12:13] offset:3072
	s_add_u32 s12, s12, 0x100000
	s_addc_u32 s13, s13, 0
	global_load_dwordx4 v[116:119], v3, s[12:13]
	global_load_dwordx4 v[120:123], v3, s[12:13] offset:1024
	global_load_dwordx4 v[124:127], v3, s[12:13] offset:2048
	global_load_dwordx4 v[128:131], v3, s[12:13] offset:3072
	s_add_u32 s12, s12, 0x100000
	s_addc_u32 s13, s13, 0
	global_load_dwordx4 v[132:135], v3, s[12:13]
	global_load_dwordx4 v[136:139], v3, s[12:13] offset:1024
	global_load_dwordx4 v[140:143], v3, s[12:13] offset:2048
	global_load_dwordx4 v[144:147], v3, s[12:13] offset:3072
	s_add_i32 s14, s4, 0x4000
	s_mul_i32 s14, s14, 0x2800
	s_add_u32 s14, s8, s14
	s_addc_u32 s15, s9, 0
	s_add_u32 s14, s14, 0x66c9000
	s_addc_u32 s15, s15, 0
	s_waitcnt vmcnt(24)
	v_pk_add_f32 v[20:21], v[20:21], v[36:37]
	v_pk_add_f32 v[22:23], v[22:23], v[38:39]
	v_pk_add_f32 v[24:25], v[24:25], v[40:41]
	v_pk_add_f32 v[26:27], v[26:27], v[42:43]
	v_pk_add_f32 v[28:29], v[28:29], v[44:45]
	v_pk_add_f32 v[30:31], v[30:31], v[46:47]
	v_pk_add_f32 v[32:33], v[32:33], v[48:49]
	v_pk_add_f32 v[34:35], v[34:35], v[50:51]
	s_waitcnt vmcnt(20)
	v_pk_add_f32 v[20:21], v[20:21], v[52:53]
	v_pk_add_f32 v[22:23], v[22:23], v[54:55]
	v_pk_add_f32 v[24:25], v[24:25], v[56:57]
	v_pk_add_f32 v[26:27], v[26:27], v[58:59]
	v_pk_add_f32 v[28:29], v[28:29], v[60:61]
	v_pk_add_f32 v[30:31], v[30:31], v[62:63]
	v_pk_add_f32 v[32:33], v[32:33], v[64:65]
	v_pk_add_f32 v[34:35], v[34:35], v[66:67]
	s_waitcnt vmcnt(16)
	v_pk_add_f32 v[20:21], v[20:21], v[68:69]
	v_pk_add_f32 v[22:23], v[22:23], v[70:71]
	v_pk_add_f32 v[24:25], v[24:25], v[72:73]
	v_pk_add_f32 v[26:27], v[26:27], v[74:75]
	v_pk_add_f32 v[28:29], v[28:29], v[76:77]
	v_pk_add_f32 v[30:31], v[30:31], v[78:79]
	v_pk_add_f32 v[32:33], v[32:33], v[80:81]
	v_pk_add_f32 v[34:35], v[34:35], v[82:83]
	s_waitcnt vmcnt(12)
	v_pk_add_f32 v[20:21], v[20:21], v[84:85]
	v_pk_add_f32 v[22:23], v[22:23], v[86:87]
	v_pk_add_f32 v[24:25], v[24:25], v[88:89]
	v_pk_add_f32 v[26:27], v[26:27], v[90:91]
	v_pk_add_f32 v[28:29], v[28:29], v[92:93]
	v_pk_add_f32 v[30:31], v[30:31], v[94:95]
	v_pk_add_f32 v[32:33], v[32:33], v[96:97]
	v_pk_add_f32 v[34:35], v[34:35], v[98:99]
	s_waitcnt vmcnt(8)
	v_pk_add_f32 v[20:21], v[20:21], v[100:101]
	v_pk_add_f32 v[22:23], v[22:23], v[102:103]
	v_pk_add_f32 v[24:25], v[24:25], v[104:105]
	v_pk_add_f32 v[26:27], v[26:27], v[106:107]
	v_pk_add_f32 v[28:29], v[28:29], v[108:109]
	v_pk_add_f32 v[30:31], v[30:31], v[110:111]
	v_pk_add_f32 v[32:33], v[32:33], v[112:113]
	v_pk_add_f32 v[34:35], v[34:35], v[114:115]
	s_waitcnt vmcnt(4)
	v_pk_add_f32 v[20:21], v[20:21], v[116:117]
	v_pk_add_f32 v[22:23], v[22:23], v[118:119]
	v_pk_add_f32 v[24:25], v[24:25], v[120:121]
	v_pk_add_f32 v[26:27], v[26:27], v[122:123]
	v_pk_add_f32 v[28:29], v[28:29], v[124:125]
	v_pk_add_f32 v[30:31], v[30:31], v[126:127]
	v_pk_add_f32 v[32:33], v[32:33], v[128:129]
	v_pk_add_f32 v[34:35], v[34:35], v[130:131]
	s_waitcnt vmcnt(0)
	v_pk_add_f32 v[20:21], v[20:21], v[132:133]
	v_pk_add_f32 v[22:23], v[22:23], v[134:135]
	v_pk_add_f32 v[24:25], v[24:25], v[136:137]
	v_pk_add_f32 v[26:27], v[26:27], v[138:139]
	v_pk_add_f32 v[28:29], v[28:29], v[140:141]
	v_pk_add_f32 v[30:31], v[30:31], v[142:143]
	v_pk_add_f32 v[32:33], v[32:33], v[144:145]
	v_pk_add_f32 v[34:35], v[34:35], v[146:147]
	v_cvt_pk_bf16_f32 v150, v20, v21
	v_cvt_pk_bf16_f32 v151, v22, v23
	global_store_dwordx2 v5, v[150:151], s[14:15] sc0 sc1
	v_cvt_pk_bf16_f32 v152, v24, v25
	v_cvt_pk_bf16_f32 v153, v26, v27
	global_store_dwordx2 v5, v[152:153], s[14:15] offset:512 sc0 sc1
	v_cvt_pk_bf16_f32 v154, v28, v29
	v_cvt_pk_bf16_f32 v155, v30, v31
	global_store_dwordx2 v5, v[154:155], s[14:15] offset:1024 sc0 sc1
	v_cvt_pk_bf16_f32 v156, v32, v33
	v_cvt_pk_bf16_f32 v157, v34, v35
	global_store_dwordx2 v5, v[156:157], s[14:15] offset:1536 sc0 sc1
	s_add_i32 s4, s4, s6
	s_cmpk_lt_i32 s4, 0x100
	s_cbranch_scc1 .LBB0_641
; #define LAS __attribute__((address_space(3)))
; __device__ __forceinline__ KP kargs() { KP k = (KP)__builtin_amdgcn_kernarg_segment_ptr(); asm volatile("" : "+s"(k)); return k; }
; __device__ __forceinline__ int tid_() { int t = threadIdx.x; asm volatile("" : "+v"(t)); return t; }
; __device__ __forceinline__ int bid_() { int t = blockIdx.x; asm volatile("" : "+s"(t)); return t; }
;         nmain = c < nwg ? (nwg - c + G - 1) / G : 0; }
; __device__ __forceinline__ void grid_barrier(LAS unsigned char* lds) {
;     asm volatile("s_waitcnt vmcnt(0)" ::: "memory");
;     __syncthreads();
;     if (tid_() == 0) {
;         unsigned* bar = (unsigned*)(kargs()->ws + WS_BAR);
;         volatile LAS unsigned* st = (volatile LAS unsigned*)(lds + LDS_BAR_OFF);
;         const unsigned x = xb_xcc_id();
;         __builtin_amdgcn_s_waitcnt(0);
;         unsigned nloc = st[0], nx = st[1];
;         if (nloc == 0u) { xcd_barrier_complete(bar, x, nloc, nx); st[0] = nloc; st[1] = nx; }
;         const unsigned old = xb_add(&bar[XB_XSUB(x)], 1u);
;         const unsigned gen = old / nloc;
;         if (old + 1u == (gen + 1u) * nloc) {
;             __builtin_amdgcn_fence(__ATOMIC_RELEASE, "agent");
;             asm volatile("s_waitcnt vmcnt(0)" ::: "memory");
;             const unsigned og = xb_add(&bar[XB_TOP], 1u);
;             const unsigned tg = og / nx;
;             if (og + 1u == (tg + 1u) * nx) xb_add(&bar[XB_TOPGEN], 1u);
;             else XB_SPIN(xb_ld(&bar[XB_TOPGEN]) == tg, bar);
;             __builtin_amdgcn_fence(__ATOMIC_ACQUIRE, "agent");
;             xb_add(&bar[XB_XGEN(x)], 1u);
;             asm volatile("s_waitcnt vmcnt(0)" ::: "memory");
;         } else {
;             XB_SPIN(xb_ld(&bar[XB_XGEN(x)]) == gen, bar);
;             __builtin_amdgcn_fence(__ATOMIC_ACQUIRE, "agent");
;             asm volatile("s_waitcnt vmcnt(0)" ::: "memory");
;         }
;     }
;     __syncthreads();
; }
; __global__ void __launch_bounds__(512, 2) fwd_megakernel(Params pv) {
;     ...
;         mixed_fold_phase(kargs());
;         grid_barrier(lds);
;         { unsigned char* ws = kargs()->ws; pg8::Gemm g{(const bf16_t*)(ws + WS_BIG) + C_MIX, nullptr, (const bf16_t*)(ws + WS_WO), nullptr, DP, D}; pg8::Order S; S.init(M, D, D, gdim_(), bid_(), 1, 4);
;           pg8::EpiRes E{(bf16_t*)(ws + WS_X), (float*)(ws + WS_SLAB), D / 64}; pg8::gemm_phase(lds, g, S, E); }
.LBB0_642:
	s_waitcnt vmcnt(0)
	v_mov_b32_e32 v0, v209
	s_barrier
	s_nop 0
	v_cmp_eq_u32_e32 vcc, 0, v0
	s_and_saveexec_b64 s[4:5], vcc
	s_cbranch_execz .LBB0_694
	v_readlane_b32 s12, v255, 8
	v_readlane_b32 s13, v255, 9
	v_mov_b32_e32 v19, 1
	v_mov_b32_e32 v22, 0
	s_lshl_b32 s35, s56, 4
	s_add_i32 s35, s35, 15880
	s_add_u32 s12, s12, s35
	s_addc_u32 s13, s13, 0
	global_atomic_add v22, v19, s[12:13]
	s_waitcnt vmcnt(0)
.LBB0_694:
	s_or_b64 exec, exec, s[4:5]
	s_mov_b64 s[4:5], s[94:95]
	s_waitcnt lgkmcnt(0)
	s_barrier
	s_cmpk_gt_u32 s2, 15
	s_cbranch_scc1 .Lfw_p6_done
	v_readlane_b32 s12, v255, 8
	v_readlane_b32 s13, v255, 9
	s_lshl_b32 s14, s56, 4
	s_add_i32 s14, s14, 15880
	v_mov_b32_e32 v18, 0
	s_add_u32 s12, s12, s14
	s_addc_u32 s13, s13, 0
	s_mov_b32 s14, 0
.Lfw_p6_loop:
	global_load_dword v19, v18, s[12:13] sc0 sc1
	s_waitcnt vmcnt(0)
	v_readfirstlane_b32 s15, v19
	s_nop 3
	s_cmpk_ge_u32 s15, 0x100
	s_cbranch_scc1 .Lfw_p6_done
	s_sleep 1
	s_add_i32 s14, s14, 1
	s_cmp_lt_u32 s14, 0x100000
	s_cbranch_scc1 .Lfw_p6_loop
.Lfw_p6_done:
	s_load_dwordx2 s[4:5], s[4:5], 0xe8
	s_mov_b32 s16, s3
	s_mov_b32 s18, s2
	s_cmpk_gt_i32 s18, 0xff
	s_mov_b32 s19, 0
	s_cbranch_scc1 .LBB0_696
	s_abs_i32 s6, s16
	v_cvt_f32_u32_e32 v0, s6
	s_not_b32 s7, s18
	s_add_i32 s7, s16, s7
	s_add_i32 s9, s7, 0x100
	v_rcp_iflag_f32_e32 v0, v0
	s_sub_i32 s7, 0xffffff00, s7
	s_xor_b32 s10, s9, s16
	s_sub_i32 s8, 0, s6
	v_mul_f32_e32 v0, 0x4f7ffffe, v0
	v_cvt_u32_f32_e32 v0, v0
	s_max_i32 s7, s9, s7
	s_ashr_i32 s9, s10, 31
	v_readfirstlane_b32 s10, v0
	s_mul_i32 s8, s8, s10
	s_mul_hi_u32 s8, s10, s8
	s_add_i32 s10, s10, s8
	s_mul_hi_u32 s8, s7, s10
	s_mul_i32 s10, s8, s6
	s_sub_i32 s7, s7, s10
	s_add_i32 s11, s8, 1
	s_sub_i32 s10, s7, s6
	s_cmp_ge_u32 s7, s6
	s_cselect_b32 s8, s11, s8
	s_cselect_b32 s7, s10, s7
	s_add_i32 s10, s8, 1
	s_cmp_ge_u32 s7, s6
	s_cselect_b32 s6, s10, s8
	s_xor_b32 s6, s6, s9
	s_sub_i32 s19, s6, s9

; #define LAS __attribute__((address_space(3)))
; __device__ __forceinline__ KP kargs() { KP k = (KP)__builtin_amdgcn_kernarg_segment_ptr(); asm volatile("" : "+s"(k)); return k; }
; __device__ __forceinline__ int tid_() { int t = threadIdx.x; asm volatile("" : "+v"(t)); return t; }
; __device__ __forceinline__ unsigned xb_ld(unsigned* p)              { return __hip_atomic_load(p, __ATOMIC_RELAXED, __HIP_MEMORY_SCOPE_AGENT); }
; __device__ __forceinline__ unsigned xb_add(unsigned* p, unsigned v) { return __hip_atomic_fetch_add(p, v, __ATOMIC_RELAXED, __HIP_MEMORY_SCOPE_AGENT); }
; __device__ __forceinline__ unsigned xb_xcc_id() { return (unsigned)__builtin_amdgcn_s_getreg((3 << 11) | 20) & 0xFu; }
; __device__ __forceinline__ void grid_barrier(LAS unsigned char* lds) {
;     asm volatile("s_waitcnt vmcnt(0)" ::: "memory");
;     __syncthreads();
;     if (tid_() == 0) {
;         unsigned* bar = (unsigned*)(kargs()->ws + WS_BAR);
;         volatile LAS unsigned* st = (volatile LAS unsigned*)(lds + LDS_BAR_OFF);
;         const unsigned x = xb_xcc_id();
;         __builtin_amdgcn_s_waitcnt(0);
;         unsigned nloc = st[0], nx = st[1];
;         if (nloc == 0u) { xcd_barrier_complete(bar, x, nloc, nx); st[0] = nloc; st[1] = nx; }
;         const unsigned old = xb_add(&bar[XB_XSUB(x)], 1u);
;         const unsigned gen = old / nloc;
;         if (old + 1u == (gen + 1u) * nloc) {
;             __builtin_amdgcn_fence(__ATOMIC_RELEASE, "agent");
;             asm volatile("s_waitcnt vmcnt(0)" ::: "memory");
;             const unsigned og = xb_add(&bar[XB_TOP], 1u);
;             const unsigned tg = og / nx;
;             if (og + 1u == (tg + 1u) * nx) xb_add(&bar[XB_TOPGEN], 1u);
;             else XB_SPIN(xb_ld(&bar[XB_TOPGEN]) == tg, bar);
;             __builtin_amdgcn_fence(__ATOMIC_ACQUIRE, "agent");
;             xb_add(&bar[XB_XGEN(x)], 1u);
;             asm volatile("s_waitcnt vmcnt(0)" ::: "memory");
;         } else {
;             XB_SPIN(xb_ld(&bar[XB_XGEN(x)]) == gen, bar);
;             __builtin_amdgcn_fence(__ATOMIC_ACQUIRE, "agent");
;             asm volatile("s_waitcnt vmcnt(0)" ::: "memory");
;         }
;     }
;     __syncthreads();
; }
; __global__ void __launch_bounds__(512, 2) fwd_megakernel(Params pv) {
;     ...
;         grid_barrier(lds);
.LBB0_738:
	s_waitcnt vmcnt(0)
	v_mov_b32_e32 v0, v209
	s_waitcnt vmcnt(0) lgkmcnt(0)
	s_barrier
	s_nop 0
	v_cmp_eq_u32_e32 vcc, 0, v0
	s_and_saveexec_b64 s[4:5], vcc
	s_cbranch_execz .LBB0_790
	v_readlane_b32 s12, v255, 8
	v_readlane_b32 s13, v255, 9
	v_mov_b32_e32 v18, 0x20000
	ds_read2_b32 v[20:21], v18 offset1:1
	s_getreg_b32 s14, hwreg(HW_REG_XCC_ID, 0, 4)
	s_and_b32 s14, s14, 15
	s_mul_i32 s32, s56, 8
	s_add_i32 s32, s32, 5
	s_add_i32 s34, s32, 1
	v_mov_b32_e32 v19, 1
	v_mov_b32_e32 v22, 0
	s_waitcnt lgkmcnt(0)
	v_readfirstlane_b32 s24, v20
	v_readfirstlane_b32 s25, v21
	s_lshl_b32 s35, s14, 8
	s_add_u32 s70, s12, s35
	s_addc_u32 s71, s13, 0
	s_add_u32 s72, s70, 0x2400
	s_addc_u32 s73, s71, 0
	s_add_u32 s70, s70, 0x1400
	s_addc_u32 s71, s71, 0
	global_atomic_add v23, v22, v19, s[70:71] sc0
	s_mul_i32 s57, s34, s24
	s_waitcnt vmcnt(0)
	v_readfirstlane_b32 s44, v23
	s_nop 3
	s_add_i32 s44, s44, 1
	s_cmp_lg_u32 s44, s57
	s_cbranch_scc1 .Lfb7_spin
	buffer_wbl2 sc1
	s_waitcnt vmcnt(0)
	s_add_u32 s98, s12, 0x3400
	s_addc_u32 s99, s13, 0
	global_atomic_add v23, v22, v19, s[98:99] sc0
	s_mul_i32 s57, s34, s25
	s_waitcnt vmcnt(0)
	v_readfirstlane_b32 s44, v23
	s_nop 3
	s_add_i32 s44, s44, 1
	s_cmp_lg_u32 s44, s57
	s_cbranch_scc1 .Lfb7_spin
	global_atomic_add v22, v19, s[98:99] offset:256
	s_add_u32 s98, s12, 0x2400
	s_addc_u32 s99, s13, 0
	global_atomic_add v22, v19, s[98:99]
	global_atomic_add v22, v19, s[98:99] offset:256
	global_atomic_add v22, v19, s[98:99] offset:512
	global_atomic_add v22, v19, s[98:99] offset:768
	global_atomic_add v22, v19, s[98:99] offset:1024
	global_atomic_add v22, v19, s[98:99] offset:1280
	global_atomic_add v22, v19, s[98:99] offset:1536
	global_atomic_add v22, v19, s[98:99] offset:1792
	global_atomic_add v22, v19, s[98:99] offset:2048
	global_atomic_add v22, v19, s[98:99] offset:2304
	global_atomic_add v22, v19, s[98:99] offset:2560
	global_atomic_add v22, v19, s[98:99] offset:2816
	global_atomic_add v22, v19, s[98:99] offset:3072
	global_atomic_add v22, v19, s[98:99] offset:3328
	global_atomic_add v22, v19, s[98:99] offset:3584
	global_atomic_add v22, v19, s[98:99] offset:3840

; __device__ __forceinline__ KP kargs() { KP k = (KP)__builtin_amdgcn_kernarg_segment_ptr(); asm volatile("" : "+s"(k)); return k; }
; __global__ void __launch_bounds__(512, 2) fwd_megakernel(Params pv) {
;     ...
;         norm_phase(kargs(), false, 4);
;         grid_barrier(lds);
.LBB0_807:
	s_waitcnt vmcnt(0)
	v_mov_b32_e32 v0, v209
	s_barrier
	s_nop 0
	v_cmp_eq_u32_e32 vcc, 0, v0
	s_and_saveexec_b64 s[4:5], vcc
	s_cbranch_execz .LBB0_859
	v_readlane_b32 s12, v255, 8
	v_readlane_b32 s13, v255, 9
	v_mov_b32_e32 v19, 1
	v_mov_b32_e32 v22, 0
	s_lshl_b32 s35, s56, 4
	s_add_i32 s35, s35, 15876
	s_add_u32 s12, s12, s35
	s_addc_u32 s13, s13, 0
	global_atomic_add v22, v19, s[12:13]
	s_waitcnt vmcnt(0)

;     __device__ __forceinline__ void operator()(const f32x4 (&acc)[2][2][4][2], const Unit& u, int wr, int wc, int fr, int fq) const {
;         const int ch0 = u.pn * 128 + wc * 32 + 8 * fq;
;         float w0[8], w1[8], w2[8], bb[8]; load8f(cw + ch0, w0); load8f(cw + DFF + ch0, w1); load8f(cw + 2 * DFF + ch0, w2); load8f(cb + ch0, bb);
;         const int rbase = u.pm * BM + wr * 64 + fr;
;         const int b0 = (u.pm * BM) / TP, rb = (b0 + 1) * TP;
.LBB0_883:
	v_lshl_or_b32 v174, s10, 7, v181
	v_lshlrev_b32_e32 v176, 2, v174
	s_lshl_b32 s91, s90, 8
	global_load_dwordx4 v[50:53], v176, s[66:67]
	global_load_dwordx4 v[54:57], v176, s[66:67] offset:16
	global_load_dwordx4 v[58:61], v176, s[78:79]
	global_load_dwordx4 v[62:65], v176, s[78:79] offset:16
	global_load_dwordx4 v[66:69], v176, s[80:81]
	global_load_dwordx4 v[70:73], v176, s[80:81] offset:16
	global_load_dwordx4 v[74:77], v176, s[68:69]
	global_load_dwordx4 v[78:81], v176, s[68:69] offset:16
	s_mul_hi_u32 s35, s91, 0xfe03f81
	s_lshr_b32 s35, s35, 7
	s_add_i32 s54, s35, 1
	s_mul_i32 s85, s54, 0x810
	s_add_i32 s91, s91, s18
	v_mul_u32_u24_e32 v183, s22, v178
	v_lshl_add_u32 v183, v174, 1, v183
	v_mul_u32_u24_e32 v236, s39, v178
	v_lshl_add_u32 v236, v174, 1, v236
	v_add_u32_e32 v237, s22, v236
	v_mul_i32_i24_e32 v238, s22, v180
	v_lshl_add_u32 v238, v174, 1, v238
	v_mul_i32_i24_e32 v239, s39, v180
	v_lshl_add_u32 v239, v174, 2, v239
	v_mul_u32_u24_e32 v248, 0x5800, v178
	v_lshl_add_u32 v248, v174, 2, v248
	s_cmp_lg_u32 s21, 0
	s_cbranch_scc1 .Lfw_p8_done
	s_lshl_b32 s10, s56, 4
	s_add_u32 s94, s60, 0x13ce3e04
	s_addc_u32 s95, s61, 0
	s_add_u32 s94, s94, s10
	s_addc_u32 s95, s95, 0
	v_mov_b32_e32 v249, 0
	s_mov_b32 s10, 0

; #define LAS __attribute__((address_space(3)))
; __device__ __forceinline__ KP kargs() { KP k = (KP)__builtin_amdgcn_kernarg_segment_ptr(); asm volatile("" : "+s"(k)); return k; }
; __device__ __forceinline__ int tid_() { int t = threadIdx.x; asm volatile("" : "+v"(t)); return t; }
; __device__ __forceinline__ unsigned xb_ld(unsigned* p)              { return __hip_atomic_load(p, __ATOMIC_RELAXED, __HIP_MEMORY_SCOPE_AGENT); }
; __device__ __forceinline__ unsigned xb_add(unsigned* p, unsigned v) { return __hip_atomic_fetch_add(p, v, __ATOMIC_RELAXED, __HIP_MEMORY_SCOPE_AGENT); }
; __device__ __forceinline__ unsigned xb_xcc_id() { return (unsigned)__builtin_amdgcn_s_getreg((3 << 11) | 20) & 0xFu; }
; __device__ __forceinline__ void grid_barrier(LAS unsigned char* lds) {
;     asm volatile("s_waitcnt vmcnt(0)" ::: "memory");
;     __syncthreads();
;     if (tid_() == 0) {
;         unsigned* bar = (unsigned*)(kargs()->ws + WS_BAR);
;         volatile LAS unsigned* st = (volatile LAS unsigned*)(lds + LDS_BAR_OFF);
;         const unsigned x = xb_xcc_id();
;         __builtin_amdgcn_s_waitcnt(0);
;         unsigned nloc = st[0], nx = st[1];
;         if (nloc == 0u) { xcd_barrier_complete(bar, x, nloc, nx); st[0] = nloc; st[1] = nx; }
;         const unsigned old = xb_add(&bar[XB_XSUB(x)], 1u);
;         const unsigned gen = old / nloc;
;         if (old + 1u == (gen + 1u) * nloc) {
;             __builtin_amdgcn_fence(__ATOMIC_RELEASE, "agent");
;             asm volatile("s_waitcnt vmcnt(0)" ::: "memory");
;             const unsigned og = xb_add(&bar[XB_TOP], 1u);
;             const unsigned tg = og / nx;
;             if (og + 1u == (tg + 1u) * nx) xb_add(&bar[XB_TOPGEN], 1u);
;             else XB_SPIN(xb_ld(&bar[XB_TOPGEN]) == tg, bar);
;             __builtin_amdgcn_fence(__ATOMIC_ACQUIRE, "agent");
;             xb_add(&bar[XB_XGEN(x)], 1u);
;             asm volatile("s_waitcnt vmcnt(0)" ::: "memory");
;         } else {
;             XB_SPIN(xb_ld(&bar[XB_XGEN(x)]) == gen, bar);
;             __builtin_amdgcn_fence(__ATOMIC_ACQUIRE, "agent");
;             asm volatile("s_waitcnt vmcnt(0)" ::: "memory");
;         }
;     }
;     __syncthreads();
; }
; __global__ void __launch_bounds__(512, 2) fwd_megakernel(Params pv) {
;     ...
;         grid_barrier(lds);
.LBB0_956:
	s_waitcnt vmcnt(0)
	v_mov_b32_e32 v0, v209
	s_waitcnt lgkmcnt(0)
	s_barrier
	s_nop 0
	v_cmp_eq_u32_e32 vcc, 0, v0
	s_and_saveexec_b64 s[4:5], vcc
	v_readlane_b32 s0, v255, 1
	s_mov_b32 s90, 0x62000
	s_mov_b32 s94, 0x69000
	s_mov_b32 s95, 0x70000
	s_mov_b32 s20, 0x77000
	v_readlane_b32 s1, v255, 2
	s_mov_b32 s96, 0x8c000
	s_mov_b32 s21, 0xfe03f81
	s_cbranch_execz .LBB0_1008
	v_readlane_b32 s12, v255, 8
	v_readlane_b32 s13, v255, 9
	v_mov_b32_e32 v18, 0x20000
	ds_read2_b32 v[20:21], v18 offset1:1
	s_getreg_b32 s14, hwreg(HW_REG_XCC_ID, 0, 4)
	s_and_b32 s14, s14, 15
	s_mul_i32 s32, s86, 8
	s_add_i32 s32, s32, -2
	s_add_i32 s34, s32, 1
	v_mov_b32_e32 v19, 1
	v_mov_b32_e32 v22, 0
	s_waitcnt lgkmcnt(0)
	v_readfirstlane_b32 s24, v20
	v_readfirstlane_b32 s25, v21
	s_lshl_b32 s35, s14, 8
	s_add_u32 s70, s12, s35
	s_addc_u32 s71, s13, 0
	s_add_u32 s72, s70, 0x2400
	s_addc_u32 s73, s71, 0
	s_add_u32 s70, s70, 0x1400
	s_addc_u32 s71, s71, 0
	global_atomic_add v23, v22, v19, s[70:71] sc0
	s_mul_i32 s57, s34, s24
	s_waitcnt vmcnt(0)
	v_readfirstlane_b32 s44, v23
	s_nop 3
	s_add_i32 s44, s44, 1
	s_cmp_lg_u32 s44, s57
	s_cbranch_scc1 .Lfb9_spin
	buffer_wbl2 sc1
	s_waitcnt vmcnt(0)
	s_add_u32 s98, s12, 0x3400
	s_addc_u32 s99, s13, 0
	global_atomic_add v23, v22, v19, s[98:99] sc0
	s_mul_i32 s57, s34, s25
	s_waitcnt vmcnt(0)
	v_readfirstlane_b32 s44, v23
	s_nop 3
	s_add_i32 s44, s44, 1
	s_cmp_lg_u32 s44, s57
	s_cbranch_scc1 .Lfb9_spin
	global_atomic_add v22, v19, s[98:99] offset:256
	s_add_u32 s98, s12, 0x2400
	s_addc_u32 s99, s13, 0
	global_atomic_add v22, v19, s[98:99]
	global_atomic_add v22, v19, s[98:99] offset:256
	global_atomic_add v22, v19, s[98:99] offset:512
	global_atomic_add v22, v19, s[98:99] offset:768
	global_atomic_add v22, v19, s[98:99] offset:1024
	global_atomic_add v22, v19, s[98:99] offset:1280
	global_atomic_add v22, v19, s[98:99] offset:1536
	global_atomic_add v22, v19, s[98:99] offset:1792
	global_atomic_add v22, v19, s[98:99] offset:2048
	global_atomic_add v22, v19, s[98:99] offset:2304
	global_atomic_add v22, v19, s[98:99] offset:2560
	global_atomic_add v22, v19, s[98:99] offset:2816
	global_atomic_add v22, v19, s[98:99] offset:3072
	global_atomic_add v22, v19, s[98:99] offset:3328
	global_atomic_add v22, v19, s[98:99] offset:3584
	global_atomic_add v22, v19, s[98:99] offset:3840

; #define LAS __attribute__((address_space(3)))
; __device__ __forceinline__ KP kargs() { KP k = (KP)__builtin_amdgcn_kernarg_segment_ptr(); asm volatile("" : "+s"(k)); return k; }
; __device__ __forceinline__ int tid_() { int t = threadIdx.x; asm volatile("" : "+v"(t)); return t; }
; __device__ __forceinline__ unsigned xb_ld(unsigned* p)              { return __hip_atomic_load(p, __ATOMIC_RELAXED, __HIP_MEMORY_SCOPE_AGENT); }
; __device__ __forceinline__ unsigned xb_add(unsigned* p, unsigned v) { return __hip_atomic_fetch_add(p, v, __ATOMIC_RELAXED, __HIP_MEMORY_SCOPE_AGENT); }
; __device__ __forceinline__ unsigned xb_xcc_id() { return (unsigned)__builtin_amdgcn_s_getreg((3 << 11) | 20) & 0xFu; }
; __device__ __forceinline__ void grid_barrier(LAS unsigned char* lds) {
;     asm volatile("s_waitcnt vmcnt(0)" ::: "memory");
;     __syncthreads();
;     if (tid_() == 0) {
;         unsigned* bar = (unsigned*)(kargs()->ws + WS_BAR);
;         volatile LAS unsigned* st = (volatile LAS unsigned*)(lds + LDS_BAR_OFF);
;         const unsigned x = xb_xcc_id();
;         __builtin_amdgcn_s_waitcnt(0);
;         unsigned nloc = st[0], nx = st[1];
;         if (nloc == 0u) { xcd_barrier_complete(bar, x, nloc, nx); st[0] = nloc; st[1] = nx; }
;         const unsigned old = xb_add(&bar[XB_XSUB(x)], 1u);
;         const unsigned gen = old / nloc;
;         if (old + 1u == (gen + 1u) * nloc) {
;             __builtin_amdgcn_fence(__ATOMIC_RELEASE, "agent");
;             asm volatile("s_waitcnt vmcnt(0)" ::: "memory");
;             const unsigned og = xb_add(&bar[XB_TOP], 1u);
;             const unsigned tg = og / nx;
;             if (og + 1u == (tg + 1u) * nx) xb_add(&bar[XB_TOPGEN], 1u);
;             else XB_SPIN(xb_ld(&bar[XB_TOPGEN]) == tg, bar);
;             __builtin_amdgcn_fence(__ATOMIC_ACQUIRE, "agent");
;             xb_add(&bar[XB_XGEN(x)], 1u);
;             asm volatile("s_waitcnt vmcnt(0)" ::: "memory");
;         } else {
;             XB_SPIN(xb_ld(&bar[XB_XGEN(x)]) == gen, bar);
;             __builtin_amdgcn_fence(__ATOMIC_ACQUIRE, "agent");
;             asm volatile("s_waitcnt vmcnt(0)" ::: "memory");
;         }
;     }
;     __syncthreads();
; }
; __global__ void __launch_bounds__(512, 2) fwd_megakernel(Params pv) {
;     ...
;         grid_barrier(lds);
.LBB0_1015:
	s_or_b64 exec, exec, s[4:5]
	s_waitcnt vmcnt(0)
	v_mov_b32_e32 v0, v209
	s_barrier
	s_nop 0
	v_cmp_eq_u32_e32 vcc, 0, v0
	s_and_saveexec_b64 s[4:5], vcc
	s_mov_b32 s43, 0x54000
	s_mov_b32 s87, 0x5b000
	s_cbranch_execz .LBB0_1067
	v_readlane_b32 s12, v255, 8
	v_readlane_b32 s13, v255, 9
	v_mov_b32_e32 v18, 0x20000
	ds_read2_b32 v[20:21], v18 offset1:1
	s_getreg_b32 s14, hwreg(HW_REG_XCC_ID, 0, 4)
	s_and_b32 s14, s14, 15
	s_mul_i32 s32, s86, 8
	s_add_i32 s32, s32, -1
	s_add_i32 s34, s32, 1
	v_mov_b32_e32 v19, 1
	v_mov_b32_e32 v22, 0
	s_waitcnt lgkmcnt(0)
	v_readfirstlane_b32 s24, v20
	v_readfirstlane_b32 s25, v21
	s_lshl_b32 s35, s14, 8
	s_add_u32 s70, s12, s35
	s_addc_u32 s71, s13, 0
	s_add_u32 s72, s70, 0x2400
	s_addc_u32 s73, s71, 0
	s_add_u32 s70, s70, 0x1400
	s_addc_u32 s71, s71, 0
	global_atomic_add v23, v22, v19, s[70:71] sc0
	s_mul_i32 s57, s34, s24
	s_waitcnt vmcnt(0)
	v_readfirstlane_b32 s44, v23
	s_nop 3
	s_add_i32 s44, s44, 1
	s_cmp_lg_u32 s44, s57
	s_cbranch_scc1 .Lfb10_spin
	buffer_wbl2 sc1
	s_waitcnt vmcnt(0)
	s_add_u32 s98, s12, 0x3400
	s_addc_u32 s99, s13, 0
	global_atomic_add v23, v22, v19, s[98:99] sc0
	s_mul_i32 s57, s34, s25
	s_waitcnt vmcnt(0)
	v_readfirstlane_b32 s44, v23
	s_nop 3
	s_add_i32 s44, s44, 1
	s_cmp_lg_u32 s44, s57
	s_cbranch_scc1 .Lfb10_spin
	global_atomic_add v22, v19, s[98:99] offset:256
	s_add_u32 s98, s12, 0x2400
	s_addc_u32 s99, s13, 0
	global_atomic_add v22, v19, s[98:99]
	global_atomic_add v22, v19, s[98:99] offset:256
	global_atomic_add v22, v19, s[98:99] offset:512
	global_atomic_add v22, v19, s[98:99] offset:768
	global_atomic_add v22, v19, s[98:99] offset:1024
	global_atomic_add v22, v19, s[98:99] offset:1280
	global_atomic_add v22, v19, s[98:99] offset:1536
	global_atomic_add v22, v19, s[98:99] offset:1792
	global_atomic_add v22, v19, s[98:99] offset:2048
	global_atomic_add v22, v19, s[98:99] offset:2304
	global_atomic_add v22, v19, s[98:99] offset:2560
	global_atomic_add v22, v19, s[98:99] offset:2816
	global_atomic_add v22, v19, s[98:99] offset:3072
	global_atomic_add v22, v19, s[98:99] offset:3328
	global_atomic_add v22, v19, s[98:99] offset:3584
	global_atomic_add v22, v19, s[98:99] offset:3840

; #define LAS __attribute__((address_space(3)))
; __device__ __forceinline__ KP kargs() { KP k = (KP)__builtin_amdgcn_kernarg_segment_ptr(); asm volatile("" : "+s"(k)); return k; }
; __device__ __forceinline__ int tid_() { int t = threadIdx.x; asm volatile("" : "+v"(t)); return t; }
; __device__ __forceinline__ unsigned xb_ld(unsigned* p)              { return __hip_atomic_load(p, __ATOMIC_RELAXED, __HIP_MEMORY_SCOPE_AGENT); }
; __device__ __forceinline__ unsigned xb_add(unsigned* p, unsigned v) { return __hip_atomic_fetch_add(p, v, __ATOMIC_RELAXED, __HIP_MEMORY_SCOPE_AGENT); }
; __device__ __forceinline__ unsigned xb_xcc_id() { return (unsigned)__builtin_amdgcn_s_getreg((3 << 11) | 20) & 0xFu; }
; __device__ __forceinline__ void grid_barrier(LAS unsigned char* lds) {
;     asm volatile("s_waitcnt vmcnt(0)" ::: "memory");
;     __syncthreads();
;     if (tid_() == 0) {
;         unsigned* bar = (unsigned*)(kargs()->ws + WS_BAR);
;         volatile LAS unsigned* st = (volatile LAS unsigned*)(lds + LDS_BAR_OFF);
;         const unsigned x = xb_xcc_id();
;         __builtin_amdgcn_s_waitcnt(0);
;         unsigned nloc = st[0], nx = st[1];
;         if (nloc == 0u) { xcd_barrier_complete(bar, x, nloc, nx); st[0] = nloc; st[1] = nx; }
;         const unsigned old = xb_add(&bar[XB_XSUB(x)], 1u);
;         const unsigned gen = old / nloc;
;         if (old + 1u == (gen + 1u) * nloc) {
;             __builtin_amdgcn_fence(__ATOMIC_RELEASE, "agent");
;             asm volatile("s_waitcnt vmcnt(0)" ::: "memory");
;             const unsigned og = xb_add(&bar[XB_TOP], 1u);
;             const unsigned tg = og / nx;
;             if (og + 1u == (tg + 1u) * nx) xb_add(&bar[XB_TOPGEN], 1u);
;             else XB_SPIN(xb_ld(&bar[XB_TOPGEN]) == tg, bar);
;             __builtin_amdgcn_fence(__ATOMIC_ACQUIRE, "agent");
;             xb_add(&bar[XB_XGEN(x)], 1u);
;             asm volatile("s_waitcnt vmcnt(0)" ::: "memory");
;         } else {
;             XB_SPIN(xb_ld(&bar[XB_XGEN(x)]) == gen, bar);
;             __builtin_amdgcn_fence(__ATOMIC_ACQUIRE, "agent");
;             asm volatile("s_waitcnt vmcnt(0)" ::: "memory");
;         }
;     }
;     __syncthreads();
; }
; __global__ void __launch_bounds__(512, 2) fwd_megakernel(Params pv) {
;     ...
;         grid_barrier(lds);
.LBB0_1111:
	s_waitcnt vmcnt(0)
	v_mov_b32_e32 v0, v209
	s_waitcnt vmcnt(0) lgkmcnt(0)
	s_barrier
	s_nop 0
	v_cmp_eq_u32_e32 vcc, 0, v0
	s_and_saveexec_b64 s[4:5], vcc
	s_cbranch_execz .Lfb11_skip
	v_readlane_b32 s12, v255, 8
	v_readlane_b32 s13, v255, 9
	v_mov_b32_e32 v18, 0x20000
	ds_read2_b32 v[20:21], v18 offset1:1
	s_getreg_b32 s14, hwreg(HW_REG_XCC_ID, 0, 4)
	s_and_b32 s14, s14, 15
	s_mul_i32 s32, s86, 8
	s_add_i32 s32, s32, 0
	s_add_i32 s34, s32, 1
	v_mov_b32_e32 v19, 1
	v_mov_b32_e32 v22, 0
	s_waitcnt lgkmcnt(0)
	v_readfirstlane_b32 s24, v20
	v_readfirstlane_b32 s25, v21
	s_lshl_b32 s35, s14, 8
	s_add_u32 s70, s12, s35
	s_addc_u32 s71, s13, 0
	s_add_u32 s72, s70, 0x2400
	s_addc_u32 s73, s71, 0
	s_add_u32 s70, s70, 0x1400
	s_addc_u32 s71, s71, 0
	global_atomic_add v23, v22, v19, s[70:71] sc0
	s_mul_i32 s57, s34, s24
	s_waitcnt vmcnt(0)
	v_readfirstlane_b32 s44, v23
	s_nop 3
	s_add_i32 s44, s44, 1
	s_cmp_lg_u32 s44, s57
	s_cbranch_scc1 .Lfb11_spin
	buffer_wbl2 sc1
	s_waitcnt vmcnt(0)
	s_add_u32 s98, s12, 0x3400
	s_addc_u32 s99, s13, 0
	global_atomic_add v23, v22, v19, s[98:99] sc0
	s_mul_i32 s57, s34, s25
	s_waitcnt vmcnt(0)
	v_readfirstlane_b32 s44, v23
	s_nop 3
	s_add_i32 s44, s44, 1
	s_cmp_lg_u32 s44, s57
	s_cbranch_scc1 .Lfb11_spin
	global_atomic_add v22, v19, s[98:99] offset:256
	s_add_u32 s98, s12, 0x2400
	s_addc_u32 s99, s13, 0
	global_atomic_add v22, v19, s[98:99]
	global_atomic_add v22, v19, s[98:99] offset:256
	global_atomic_add v22, v19, s[98:99] offset:512
	global_atomic_add v22, v19, s[98:99] offset:768
	global_atomic_add v22, v19, s[98:99] offset:1024
	global_atomic_add v22, v19, s[98:99] offset:1280
	global_atomic_add v22, v19, s[98:99] offset:1536
	global_atomic_add v22, v19, s[98:99] offset:1792
	global_atomic_add v22, v19, s[98:99] offset:2048
	global_atomic_add v22, v19, s[98:99] offset:2304
	global_atomic_add v22, v19, s[98:99] offset:2560
	global_atomic_add v22, v19, s[98:99] offset:2816
	global_atomic_add v22, v19, s[98:99] offset:3072
	global_atomic_add v22, v19, s[98:99] offset:3328
	global_atomic_add v22, v19, s[98:99] offset:3584
	global_atomic_add v22, v19, s[98:99] offset:3840
